# E1 c_q rmsnorm loop fully unrolled with its four row loads in flight (on v4)
# baseline (speedup 1.0000x reference)
; __device__ __forceinline__ unsigned cvt_pk_bf16(float lo, float hi) { unsigned r; asm volatile("v_cvt_pk_bf16_f32 %0, %1, %2" : "=v"(r) : "v"(lo), "v"(hi)); return r; }
; __device__ __forceinline__ float bf2f(unsigned h) { return __uint_as_float(h << 16); }
; template <int D> __device__ __forceinline__ void norm_vec(const bf16_t* __restrict__ src, const float* __restrict__ gain, bf16_t* __restrict__ dst, const int sub) {
;     const u32x4 raw = *(const u32x4*)(src + sub * 8);
;     float v[8];
;     v[0] = bf2f(raw.x & 0xffffu); v[1] = bf2f(raw.x >> 16); v[2] = bf2f(raw.y & 0xffffu); v[3] = bf2f(raw.y >> 16);
;     v[4] = bf2f(raw.z & 0xffffu); v[5] = bf2f(raw.z >> 16); v[6] = bf2f(raw.w & 0xffffu); v[7] = bf2f(raw.w >> 16);
;     float ss = 0.f;
; #pragma unroll
;     for (int i = 0; i < 8; ++i) ss += v[i] * v[i];
; #pragma unroll
;     for (int o = 1; o < D / 8; o <<= 1) ss += __shfl_xor(ss, o);
;     const float rs = __builtin_amdgcn_rsqf(ss * (1.0f / D) + EPS);
;     const f32x4 g0 = *(const f32x4*)(gain + sub * 8), g1 = *(const f32x4*)(gain + sub * 8 + 4);
;     u32x4 w; w.x = pg8::cvt_pk_bf16(v[0] * rs * g0[0], v[1] * rs * g0[1]); w.y = pg8::cvt_pk_bf16(v[2] * rs * g0[2], v[3] * rs * g0[3]);
;     w.z = pg8::cvt_pk_bf16(v[4] * rs * g1[0], v[5] * rs * g1[1]); w.w = pg8::cvt_pk_bf16(v[6] * rs * g1[2], v[7] * rs * g1[3]);
;     *(u32x4*)(dst + sub * 8) = w;
; }
; __global__ void __launch_bounds__(512, 2) mega_fwd(KArgs a) {
;     ...
;             for (int e = gw * 64 + lane; e < T_ * 32; e += NGW * 64) {
;                 const int t = e >> 5;
;                 norm_vec<256>(RA + (size_t)t * EVEN_INP, qlg, CQKV + (size_t)t * 384, lane & 31);
;             }
.LBB0_4068:
	v_ashrrev_i32_e32 v17, 5, v16
	v_mad_i64_i32 v[18:19], s[14:15], v17, s96, v[10:11]
	global_load_dwordx4 v[28:31], v[18:19], off
	v_add_u32_e32 v44, 0x1000, v17
	v_mad_i64_i32 v[18:19], s[14:15], v44, s96, v[10:11]
	global_load_dwordx4 v[32:35], v[18:19], off
	v_add_u32_e32 v45, 0x2000, v17
	v_mad_i64_i32 v[18:19], s[14:15], v45, s96, v[10:11]
	global_load_dwordx4 v[36:39], v[18:19], off
	v_add_u32_e32 v46, 0x3000, v17
	v_mad_i64_i32 v[18:19], s[14:15], v46, s96, v[10:11]
	global_load_dwordx4 v[40:43], v[18:19], off
	s_waitcnt vmcnt(3)
	v_lshlrev_b32_e32 v22, 16, v28
	v_and_b32_e32 v28, 0xffff0000, v28
	v_mul_f32_e32 v26, v28, v28
	v_lshlrev_b32_e32 v23, 16, v29
	v_fmac_f32_e32 v26, v22, v22
	v_and_b32_e32 v29, 0xffff0000, v29
	v_fmac_f32_e32 v26, v23, v23
	v_lshlrev_b32_e32 v24, 16, v30
	v_fmac_f32_e32 v26, v29, v29
	v_and_b32_e32 v30, 0xffff0000, v30
	v_fmac_f32_e32 v26, v24, v24
	v_lshlrev_b32_e32 v25, 16, v31
	v_fmac_f32_e32 v26, v30, v30
	v_and_b32_e32 v31, 0xffff0000, v31
	v_fmac_f32_e32 v26, v25, v25
	v_fmac_f32_e32 v26, v31, v31
	ds_bpermute_b32 v27, v223, v26
	s_waitcnt lgkmcnt(0)
	v_add_f32_e32 v26, v26, v27
	ds_bpermute_b32 v27, v224, v26
	s_waitcnt lgkmcnt(0)
	v_add_f32_e32 v26, v26, v27
	ds_bpermute_b32 v27, v225, v26
	s_waitcnt lgkmcnt(0)
	v_add_f32_e32 v26, v26, v27
	ds_bpermute_b32 v27, v227, v26
	s_waitcnt lgkmcnt(0)
	v_add_f32_e32 v26, v26, v27
	ds_bpermute_b32 v27, v221, v26
	s_waitcnt lgkmcnt(0)
	v_add_f32_e32 v26, v26, v27
	v_fmamk_f32 v26, v26, 0x3b800000, v231
	v_rsq_f32_e32 v26, v26
	s_nop 0
	v_mul_f32_e32 v22, v26, v22
	v_mul_f32_e32 v28, v26, v28
	v_mul_f32_e32 v22, v2, v22
	v_mul_f32_e32 v28, v3, v28
	v_cvt_pk_bf16_f32 v28, v22, v28
	v_mul_f32_e32 v22, v26, v23
	v_mul_f32_e32 v29, v26, v29
	v_mul_f32_e32 v22, v4, v22
	v_mul_f32_e32 v29, v5, v29
	v_cvt_pk_bf16_f32 v29, v22, v29
	v_mul_f32_e32 v22, v26, v24
	v_mul_f32_e32 v30, v26, v30
	v_mul_f32_e32 v22, v6, v22
	v_mul_f32_e32 v30, v7, v30
	v_cvt_pk_bf16_f32 v30, v22, v30
	v_mul_f32_e32 v22, v26, v25
	v_mul_f32_e32 v31, v26, v31
	v_mul_f32_e32 v22, v8, v22
	v_mul_f32_e32 v31, v9, v31
	v_cvt_pk_bf16_f32 v31, v22, v31
	v_mad_i64_i32 v[22:23], s[14:15], v17, s73, v[12:13]
	global_store_dwordx4 v[22:23], v[28:31], off
	s_nop 1
	s_waitcnt vmcnt(3)
	v_lshlrev_b32_e32 v22, 16, v32
	v_and_b32_e32 v32, 0xffff0000, v32
	v_mul_f32_e32 v26, v32, v32
	v_lshlrev_b32_e32 v23, 16, v33
	v_fmac_f32_e32 v26, v22, v22
	v_and_b32_e32 v33, 0xffff0000, v33
	v_fmac_f32_e32 v26, v23, v23
	v_lshlrev_b32_e32 v24, 16, v34
	v_fmac_f32_e32 v26, v33, v33
	v_and_b32_e32 v34, 0xffff0000, v34
	v_fmac_f32_e32 v26, v24, v24
	v_lshlrev_b32_e32 v25, 16, v35
	v_fmac_f32_e32 v26, v34, v34
	v_and_b32_e32 v35, 0xffff0000, v35
	v_fmac_f32_e32 v26, v25, v25
	v_fmac_f32_e32 v26, v35, v35
	ds_bpermute_b32 v27, v223, v26
	s_waitcnt lgkmcnt(0)
	v_add_f32_e32 v26, v26, v27
	ds_bpermute_b32 v27, v224, v26
	s_waitcnt lgkmcnt(0)
	v_add_f32_e32 v26, v26, v27
	ds_bpermute_b32 v27, v225, v26
	s_waitcnt lgkmcnt(0)
	v_add_f32_e32 v26, v26, v27
	ds_bpermute_b32 v27, v227, v26
	s_waitcnt lgkmcnt(0)
	v_add_f32_e32 v26, v26, v27
	ds_bpermute_b32 v27, v221, v26
	s_waitcnt lgkmcnt(0)
	v_add_f32_e32 v26, v26, v27
	v_fmamk_f32 v26, v26, 0x3b800000, v231
	v_rsq_f32_e32 v26, v26
	s_nop 0
	v_mul_f32_e32 v22, v26, v22
	v_mul_f32_e32 v32, v26, v32
	v_mul_f32_e32 v22, v2, v22
	v_mul_f32_e32 v32, v3, v32
	v_cvt_pk_bf16_f32 v32, v22, v32
	v_mul_f32_e32 v22, v26, v23
	v_mul_f32_e32 v33, v26, v33
	v_mul_f32_e32 v22, v4, v22
	v_mul_f32_e32 v33, v5, v33
	v_cvt_pk_bf16_f32 v33, v22, v33
	v_mul_f32_e32 v22, v26, v24
	v_mul_f32_e32 v34, v26, v34
	v_mul_f32_e32 v22, v6, v22
	v_mul_f32_e32 v34, v7, v34
	v_cvt_pk_bf16_f32 v34, v22, v34
	v_mul_f32_e32 v22, v26, v25
	v_mul_f32_e32 v35, v26, v35
	v_mul_f32_e32 v22, v8, v22
	v_mul_f32_e32 v35, v9, v35
	v_cvt_pk_bf16_f32 v35, v22, v35
	v_mad_i64_i32 v[22:23], s[14:15], v44, s73, v[12:13]
	global_store_dwordx4 v[22:23], v[32:35], off
	s_nop 1
	s_waitcnt vmcnt(3)
; __device__ __forceinline__ unsigned cvt_pk_bf16(float lo, float hi) { unsigned r; asm volatile("v_cvt_pk_bf16_f32 %0, %1, %2" : "=v"(r) : "v"(lo), "v"(hi)); return r; }
; __device__ __forceinline__ float bf2f(unsigned h) { return __uint_as_float(h << 16); }
; template <int D> __device__ __forceinline__ void norm_vec(const bf16_t* __restrict__ src, const float* __restrict__ gain, bf16_t* __restrict__ dst, const int sub) {
;     const u32x4 raw = *(const u32x4*)(src + sub * 8);
;     float v[8];
;     v[0] = bf2f(raw.x & 0xffffu); v[1] = bf2f(raw.x >> 16); v[2] = bf2f(raw.y & 0xffffu); v[3] = bf2f(raw.y >> 16);
;     v[4] = bf2f(raw.z & 0xffffu); v[5] = bf2f(raw.z >> 16); v[6] = bf2f(raw.w & 0xffffu); v[7] = bf2f(raw.w >> 16);
;     float ss = 0.f;
; #pragma unroll
;     for (int i = 0; i < 8; ++i) ss += v[i] * v[i];
; #pragma unroll
;     for (int o = 1; o < D / 8; o <<= 1) ss += __shfl_xor(ss, o);
;     const float rs = __builtin_amdgcn_rsqf(ss * (1.0f / D) + EPS);
;     const f32x4 g0 = *(const f32x4*)(gain + sub * 8), g1 = *(const f32x4*)(gain + sub * 8 + 4);
;     u32x4 w; w.x = pg8::cvt_pk_bf16(v[0] * rs * g0[0], v[1] * rs * g0[1]); w.y = pg8::cvt_pk_bf16(v[2] * rs * g0[2], v[3] * rs * g0[3]);
;     w.z = pg8::cvt_pk_bf16(v[4] * rs * g1[0], v[5] * rs * g1[1]); w.w = pg8::cvt_pk_bf16(v[6] * rs * g1[2], v[7] * rs * g1[3]);
;     *(u32x4*)(dst + sub * 8) = w;
; }
	v_lshlrev_b32_e32 v22, 16, v36
	v_and_b32_e32 v36, 0xffff0000, v36
	v_mul_f32_e32 v26, v36, v36
	v_lshlrev_b32_e32 v23, 16, v37
	v_fmac_f32_e32 v26, v22, v22
	v_and_b32_e32 v37, 0xffff0000, v37
	v_fmac_f32_e32 v26, v23, v23
	v_lshlrev_b32_e32 v24, 16, v38
	v_fmac_f32_e32 v26, v37, v37
	v_and_b32_e32 v38, 0xffff0000, v38
	v_fmac_f32_e32 v26, v24, v24
	v_lshlrev_b32_e32 v25, 16, v39
	v_fmac_f32_e32 v26, v38, v38
	v_and_b32_e32 v39, 0xffff0000, v39
	v_fmac_f32_e32 v26, v25, v25
	v_fmac_f32_e32 v26, v39, v39
	ds_bpermute_b32 v27, v223, v26
	s_waitcnt lgkmcnt(0)
	v_add_f32_e32 v26, v26, v27
	ds_bpermute_b32 v27, v224, v26
	s_waitcnt lgkmcnt(0)
	v_add_f32_e32 v26, v26, v27
	ds_bpermute_b32 v27, v225, v26
	s_waitcnt lgkmcnt(0)
	v_add_f32_e32 v26, v26, v27
	ds_bpermute_b32 v27, v227, v26
	s_waitcnt lgkmcnt(0)
	v_add_f32_e32 v26, v26, v27
	ds_bpermute_b32 v27, v221, v26
	s_waitcnt lgkmcnt(0)
	v_add_f32_e32 v26, v26, v27
	v_fmamk_f32 v26, v26, 0x3b800000, v231
	v_rsq_f32_e32 v26, v26
	s_nop 0
	v_mul_f32_e32 v22, v26, v22
	v_mul_f32_e32 v36, v26, v36
	v_mul_f32_e32 v22, v2, v22
	v_mul_f32_e32 v36, v3, v36
	v_cvt_pk_bf16_f32 v36, v22, v36
	v_mul_f32_e32 v22, v26, v23
	v_mul_f32_e32 v37, v26, v37
	v_mul_f32_e32 v22, v4, v22
	v_mul_f32_e32 v37, v5, v37
	v_cvt_pk_bf16_f32 v37, v22, v37
	v_mul_f32_e32 v22, v26, v24
	v_mul_f32_e32 v38, v26, v38
	v_mul_f32_e32 v22, v6, v22
	v_mul_f32_e32 v38, v7, v38
	v_cvt_pk_bf16_f32 v38, v22, v38
	v_mul_f32_e32 v22, v26, v25
	v_mul_f32_e32 v39, v26, v39
	v_mul_f32_e32 v22, v8, v22
	v_mul_f32_e32 v39, v9, v39
	v_cvt_pk_bf16_f32 v39, v22, v39
	v_mad_i64_i32 v[22:23], s[14:15], v45, s73, v[12:13]
	global_store_dwordx4 v[22:23], v[36:39], off
	s_nop 1
	s_waitcnt vmcnt(3)
	v_lshlrev_b32_e32 v22, 16, v40
	v_and_b32_e32 v40, 0xffff0000, v40
	v_mul_f32_e32 v26, v40, v40
	v_lshlrev_b32_e32 v23, 16, v41
	v_fmac_f32_e32 v26, v22, v22
	v_and_b32_e32 v41, 0xffff0000, v41
	v_fmac_f32_e32 v26, v23, v23
	v_lshlrev_b32_e32 v24, 16, v42
	v_fmac_f32_e32 v26, v41, v41
	v_and_b32_e32 v42, 0xffff0000, v42
	v_fmac_f32_e32 v26, v24, v24
	v_lshlrev_b32_e32 v25, 16, v43
	v_fmac_f32_e32 v26, v42, v42
	v_and_b32_e32 v43, 0xffff0000, v43
	v_fmac_f32_e32 v26, v25, v25
	v_fmac_f32_e32 v26, v43, v43
	ds_bpermute_b32 v27, v223, v26
	s_waitcnt lgkmcnt(0)
	v_add_f32_e32 v26, v26, v27
	ds_bpermute_b32 v27, v224, v26
	s_waitcnt lgkmcnt(0)
	v_add_f32_e32 v26, v26, v27
	ds_bpermute_b32 v27, v225, v26
	s_waitcnt lgkmcnt(0)
	v_add_f32_e32 v26, v26, v27
	ds_bpermute_b32 v27, v227, v26
	s_waitcnt lgkmcnt(0)
	v_add_f32_e32 v26, v26, v27
	ds_bpermute_b32 v27, v221, v26
	s_waitcnt lgkmcnt(0)
	v_add_f32_e32 v26, v26, v27
	v_fmamk_f32 v26, v26, 0x3b800000, v231
	v_rsq_f32_e32 v26, v26
	s_nop 0
	v_mul_f32_e32 v22, v26, v22
	v_mul_f32_e32 v40, v26, v40
	v_mul_f32_e32 v22, v2, v22
	v_mul_f32_e32 v40, v3, v40
	v_cvt_pk_bf16_f32 v40, v22, v40
	v_mul_f32_e32 v22, v26, v23
	v_mul_f32_e32 v41, v26, v41
	v_mul_f32_e32 v22, v4, v22
	v_mul_f32_e32 v41, v5, v41
	v_cvt_pk_bf16_f32 v41, v22, v41
	v_mul_f32_e32 v22, v26, v24
	v_mul_f32_e32 v42, v26, v42
	v_mul_f32_e32 v22, v6, v22
	v_mul_f32_e32 v42, v7, v42
	v_cvt_pk_bf16_f32 v42, v22, v42
	v_mul_f32_e32 v22, v26, v25
	v_mul_f32_e32 v43, v26, v43
	v_mul_f32_e32 v22, v8, v22
	v_mul_f32_e32 v43, v9, v43
	v_cvt_pk_bf16_f32 v43, v22, v43
	v_mad_i64_i32 v[22:23], s[14:15], v46, s73, v[12:13]
	global_store_dwordx4 v[22:23], v[40:43], off
	s_nop 1
